# diff-attn tile loop unrolled by buffer parity: K/V fragment LDS addresses and DMA destinations become immediates (5 VALU + 9 SALU fewer per tile)
# baseline (speedup 1.0000x reference)
; #define LAS __attribute__((address_space(3)))
; __device__ __forceinline__ int v_rd_base(int lane) { return ((lane & 3) << 3) | (((lane >> 2) & 3) << 6) | (((lane >> 4) & 1) << 5) | (((lane >> 5) & 1) << 8); }
; __device__ __forceinline__ int swap23(int k) { return (k & ~0xC) | ((k & 4) << 1) | ((k & 8) >> 1); }
; #define A3_BAR() do { asm volatile("s_waitcnt vmcnt(0) lgkmcnt(0)" ::: "memory"); __builtin_amdgcn_s_barrier(); asm volatile("" ::: "memory"); } while (0)
; #define lane lane_id()
; __device__ __forceinline__ void attn_block3(const BlockRef& cur, char* lds, const int wid) {
;     const int lane = lane_id(), r32 = lane & 31, hi = lane >> 5;
;     const int NT = (cur.P0 + QB - 1) / KVBLK + 1;
;     const int qlo = cur.P0 + wid * QBLK, qm = qlo + r32 - 4 * hi;
;     char* V_lds = lds + A3_V; char* K_lds = lds + A3_K;
;     float* ws = (float*)(lds + A3_WS) + wid * 64; float* li_l = ws, * al_l = ws + 32;
;     const float* tb = cur.tb;
;     unsigned kgo[2], vgo[2];
; #pragma unroll
;     for (int i = 0; i < 2; ++i) { const int pc = 2 * wid + i;
;         const int row = 4 * pc + (lane >> 4), c = (lane & 15) ^ (row & 7); kgo[i] = (unsigned)(row * 256 + c * 16);
;         const int sub = 2 * pc + (lane >> 5), kk = (sub >> 2) * 8 + ((lane & 31) >> 2), k = swap23(kk), cc = (sub & 3) * 32 + (lane & 3) * 8; vgo[i] = (unsigned)(k * 256 + cc * 2); }
;     bf16x8 qr[8];
; #pragma unroll
;     for (int d0 = 0; d0 < 8; ++d0) qr[d0] = load8(cur.Q + (size_t)(wid * QBLK + r32) * D + d0 * 16 + hi * 8);
;     LAS unsigned char* ldsl = (LAS unsigned char*)lds;
;     const char* Kg = (const char*)cur.K; const char* Vg = (const char*)cur.V; const char* Vg2 = (const char*)cur.V2;
;     ...
;     A3_DMA(0);
;     A3_BAR();
;     float m_reg = -1e30f, l_reg = 0; f32x16 o[4] = {}, o2[4] = {};
;     const int vbase = (int)(uintptr_t)V_lds + v_rd_base(lane);
; __global__ void __launch_bounds__(512, 2) mega_fwd(Args args) {
;     ...
;                 __syncthreads();
;                 if (tid == 0) *qw = atomicAdd(qctr + vq, 1u);
;                 __syncthreads();
;                 const unsigned w = (unsigned)__builtin_amdgcn_readfirstlane((int)*qw);
;                 if (w >= 64u) break;
;                 att::attn_block3(refq(vq, 63 - (int)w), (char*)lds, wave);
.LBB0_447:
	s_or_b64 exec, exec, s[4:5]
	s_cmp_lg_u32 s77, -1
	s_cselect_b32 s4, s77, 0
	s_cselect_b32 s5, s11, 0
	v_mov_b32_e32 v2, s4
	v_mov_b32_e32 v3, s5
	s_waitcnt lgkmcnt(0)
	s_barrier
	flat_load_dword v0, v[2:3] sc0 sc1
	s_waitcnt vmcnt(0)
	s_mov_b64 s[4:5], -1
	s_waitcnt lgkmcnt(0)
	v_readfirstlane_b32 s6, v0
	s_cmp_gt_u32 s6, 63
	s_cbranch_scc1 .LBB0_442
	s_sub_i32 s44, 63, s6
	s_lshl_b32 s4, s44, 16
	v_mbcnt_lo_u32_b32 v239, -1, 0
	v_mbcnt_hi_u32_b32 v239, -1, v239
	s_or_b32 s4, s4, s78
	v_bfe_u32 v9, v239, 4, 2
	v_and_b32_e32 v0, 15, v239
	v_and_b32_e32 v238, 31, v239
	v_bitop3_b32 v0, v9, v0, 4 bitop3:0x36
	s_add_u32 s4, s34, s4
	v_bitop3_b32 v5, v9, v239, 15 bitop3:0x78
	v_lshlrev_b32_e32 v14, 4, v0
	v_or_b32_e32 v0, s39, v238
	s_addc_u32 s5, s35, 0
	v_and_b32_e32 v8, 63, v239
	v_bfe_u32 v2, v239, 2, 3
	v_or_b32_e32 v4, s15, v9
	v_lshlrev_b32_e32 v13, 4, v5
	v_bfe_u32 v16, v239, 5, 1
	v_lshlrev_b32_e32 v0, 8, v0
	v_bitop3_b32 v10, v2, 51, s15 bitop3:0xc8
	v_lshrrev_b32_e32 v2, 1, v239
	v_and_b32_e32 v3, 32, v239
	v_lshlrev_b32_e32 v12, 3, v8
	v_lshl_or_b32 v6, v4, 8, v13
	v_lshl_add_u64 v[4:5], s[4:5], 0, v[0:1]
	v_lshlrev_b32_e32 v0, 4, v16
	v_and_b32_e32 v11, 8, v2
	v_and_or_b32 v3, v12, 24, v3
	v_lshl_add_u64 v[4:5], v[4:5], 0, v[0:1]
	v_or3_b32 v2, v11, v10, s81
	v_lshlrev_b32_e32 v3, 1, v3
	global_load_dwordx4 v[192:195], v[4:5], off
	global_load_dwordx4 v[196:199], v[4:5], off offset:32
	global_load_dwordx4 v[200:203], v[4:5], off offset:64
	global_load_dwordx4 v[204:207], v[4:5], off offset:96
	global_load_dwordx4 v[208:211], v[4:5], off offset:128
	global_load_dwordx4 v[212:215], v[4:5], off offset:160
	global_load_dwordx4 v[216:219], v[4:5], off offset:192
	global_load_dwordx4 v[220:223], v[4:5], off offset:224
	s_mov_b32 m0, s83
	v_lshl_or_b32 v2, v2, 8, v3
	v_or_b32_e32 v3, 4, v9
	v_or_b32_e32 v3, s15, v3
	global_load_lds_dwordx4 v6, s[56:57]
	s_mov_b32 m0, s82
	v_lshl_or_b32 v15, v3, 8, v14
	v_mov_b32_e32 v3, v1
	global_load_lds_dwordx4 v2, s[58:59]
	s_add_i32 m0, s82, 0x4000
	v_lshl_add_u64 v[4:5], s[58:59], 0, v[2:3]
	global_load_lds_dwordx4 v2, s[62:63]
	s_add_i32 m0, s82, 0x10400
	v_lshl_add_u64 v[6:7], s[62:63], 0, v[2:3]
	global_load_lds_dwordx4 v15, s[56:57]
	v_lshl_add_u64 v[2:3], v[4:5], 0, s[46:47]
	s_add_i32 m0, s82, 0x400
	s_lshl_b32 s7, s44, 8
	global_load_lds_dwordx4 v[2:3], off
	v_lshl_add_u64 v[2:3], v[6:7], 0, s[46:47]
	s_add_i32 m0, s82, 0x4400
	s_lshl_b32 s4, s44, 2
	global_load_lds_dwordx4 v[2:3], off
	s_or_b32 s79, s7, s39
	s_or_b32 s87, s4, 3
	v_lshlrev_b32_e32 v3, 4, v239
	s_movk_i32 s4, 0x70
	v_and_b32_e32 v2, 0x118, v12
	v_and_b32_e32 v4, 0xc0, v3
	v_and_b32_e32 v5, 0x70, v3
	v_bitop3_b32 v242, v0, v3, s4 bitop3:0x78
	v_lshlrev_b32_e32 v3, 1, v239
	s_cmp_lg_u32 0, -1
	s_movk_i32 s4, 0x60
	v_and_or_b32 v2, v3, 32, v2
	s_cselect_b32 s7, 0, 0
	v_bitop3_b32 v243, v0, v5, 32 bitop3:0x36
	v_bitop3_b32 v244, v0, v5, 64 bitop3:0x36
	v_bitop3_b32 v245, v0, v5, s4 bitop3:0x36
	v_lshlrev_b32_e32 v5, 2, v238
	v_add3_u32 v246, v4, s7, v2
	s_lshl_b32 s7, s6, 2
	v_add_u32_e32 v2, s81, v10
	v_and_b32_e32 v4, 3, v239
	v_add_u32_e32 v237, s1, v0
	s_sub_i32 s88, 0x100, s7
	v_add_lshl_u32 v2, v2, v11, 8
	v_and_b32_e32 v3, 64, v3
	v_lshlrev_b32_e32 v4, 4, v4
	v_sub_u32_e32 v0, v5, v0
	s_lshl_b32 s7, s6, 10
	v_or3_b32 v2, v2, v3, v4
	v_mov_b32_e32 v3, v1
	v_lshlrev_b32_e32 v4, 8, v9
	v_subrev_u32_e32 v0, s7, v0
	v_lshlrev_b32_e32 v236, 2, v16
	v_mov_b32_e32 v224, v2
	v_add_u32_e32 v225, 0x80, v2
	v_add3_u32 v2, s86, v4, v13
	v_add_u32_e32 v247, s75, v0
	v_add_u32_e32 v0, s76, v238
	s_waitcnt vmcnt(0) lgkmcnt(0)
	s_barrier
	v_mov_b32_e32 v228, v2
	v_add3_u32 v2, s74, v4, v14
	v_sub_u32_e32 v0, v0, v236
	s_lshl_b32 s6, s6, 8
	v_mov_b32_e32 v14, v1
	v_mov_b32_e32 v15, v1
	v_cmp_gt_u32_e64 s[4:5], 32, v8
	v_add_u32_e32 v241, s1, v5
	v_mov_b32_e32 v230, v2
	v_subrev_u32_e32 v248, s6, v0
	v_mov_b32_e32 v0, v1
	v_mov_b32_e32 v2, v1
	v_mov_b32_e32 v4, v1
	v_mov_b32_e32 v5, v1
	v_mov_b32_e32 v6, v1
	v_mov_b32_e32 v7, v1
	v_mov_b32_e32 v8, v1
	v_mov_b32_e32 v9, v1
	v_mov_b32_e32 v10, v1
	v_mov_b32_e32 v11, v1
	v_mov_b32_e32 v12, v1
	v_mov_b32_e32 v13, v1
	v_mov_b64_e32 v[30:31], v[14:15]
	v_mov_b64_e32 v[62:63], v[14:15]
	v_mov_b64_e32 v[94:95], v[14:15]
	v_mov_b64_e32 v[126:127], v[14:15]
	v_mov_b64_e32 v[46:47], v[14:15]
	v_mov_b64_e32 v[78:79], v[14:15]
	v_mov_b64_e32 v[110:111], v[14:15]
	v_mov_b64_e32 v[142:143], v[14:15]
	v_lshlrev_b32_e32 v240, 8, v238
	s_mov_b32 s93, 0
	v_mov_b32_e32 v250, 0
	v_mov_b32_e32 v249, 0xf149f2ca
	s_movk_i32 s90, 0xb0
	s_add_u32 s68, s18, s66
	s_addc_u32 s69, s19, s67
	s_add_u32 s98, s18, s64
	s_addc_u32 s99, s19, s65
	s_add_u32 s98, s98, s48
	s_addc_u32 s99, s99, s49
	s_add_u32 s100, s18, s60
	s_addc_u32 s101, s19, s61
	s_add_u32 s100, s100, s48
	s_addc_u32 s101, s101, s49
	v_mov_b64_e32 v[28:29], v[12:13]
	v_mov_b64_e32 v[26:27], v[10:11]
	v_mov_b64_e32 v[24:25], v[8:9]
	v_mov_b64_e32 v[22:23], v[6:7]
	v_mov_b64_e32 v[20:21], v[4:5]
	v_mov_b64_e32 v[18:19], v[2:3]
	v_mov_b64_e32 v[16:17], v[0:1]
	v_mov_b64_e32 v[60:61], v[12:13]
	v_mov_b64_e32 v[58:59], v[10:11]
	v_mov_b64_e32 v[56:57], v[8:9]
	v_mov_b64_e32 v[54:55], v[6:7]
	v_mov_b64_e32 v[52:53], v[4:5]
	v_mov_b64_e32 v[50:51], v[2:3]
	v_mov_b64_e32 v[48:49], v[0:1]
	v_mov_b64_e32 v[92:93], v[12:13]
	v_mov_b64_e32 v[90:91], v[10:11]
	v_mov_b64_e32 v[88:89], v[8:9]
	v_mov_b64_e32 v[86:87], v[6:7]
	v_mov_b64_e32 v[84:85], v[4:5]
	v_mov_b64_e32 v[82:83], v[2:3]
	v_mov_b64_e32 v[80:81], v[0:1]
	v_mov_b64_e32 v[124:125], v[12:13]
	v_mov_b64_e32 v[122:123], v[10:11]
	v_mov_b64_e32 v[120:121], v[8:9]
	v_mov_b64_e32 v[118:119], v[6:7]
	v_mov_b64_e32 v[116:117], v[4:5]
	v_mov_b64_e32 v[114:115], v[2:3]
	v_mov_b64_e32 v[112:113], v[0:1]
	v_mov_b64_e32 v[44:45], v[12:13]
	v_mov_b64_e32 v[42:43], v[10:11]
	v_mov_b64_e32 v[40:41], v[8:9]
	v_mov_b64_e32 v[38:39], v[6:7]
	v_mov_b64_e32 v[36:37], v[4:5]
	v_mov_b64_e32 v[34:35], v[2:3]
	v_mov_b64_e32 v[32:33], v[0:1]
	v_mov_b64_e32 v[76:77], v[12:13]
	v_mov_b64_e32 v[74:75], v[10:11]
	v_mov_b64_e32 v[72:73], v[8:9]
	v_mov_b64_e32 v[70:71], v[6:7]
	v_mov_b64_e32 v[68:69], v[4:5]
	v_mov_b64_e32 v[66:67], v[2:3]
	v_mov_b64_e32 v[64:65], v[0:1]
	v_mov_b64_e32 v[108:109], v[12:13]
	v_mov_b64_e32 v[106:107], v[10:11]
	v_mov_b64_e32 v[104:105], v[8:9]
	v_mov_b64_e32 v[102:103], v[6:7]
	v_mov_b64_e32 v[100:101], v[4:5]
	v_mov_b64_e32 v[98:99], v[2:3]
	v_mov_b64_e32 v[96:97], v[0:1]
	v_mov_b64_e32 v[140:141], v[12:13]
	v_mov_b64_e32 v[138:139], v[10:11]
	v_mov_b64_e32 v[136:137], v[8:9]
	v_mov_b64_e32 v[134:135], v[6:7]
	v_mov_b64_e32 v[132:133], v[4:5]
	v_mov_b64_e32 v[130:131], v[2:3]
	v_mov_b64_e32 v[128:129], v[0:1]
	s_mov_b32 s7, 0x10000
	v_add3_u32 v252, s7, v242, v240
	v_add3_u32 v253, s7, v243, v240
	v_add3_u32 v254, s7, v244, v240
	v_add3_u32 v255, s7, v245, v240
	s_waitcnt vmcnt(0)
; #define SBAR() __builtin_amdgcn_sched_barrier(0)
; __device__ __forceinline__ int v_rd_base(int lane) { return ((lane & 3) << 3) | (((lane >> 2) & 3) << 6) | (((lane >> 4) & 1) << 5) | (((lane >> 5) & 1) << 8); }
; #define A3_BAR() do { asm volatile("s_waitcnt vmcnt(0) lgkmcnt(0)" ::: "memory"); __builtin_amdgcn_s_barrier(); asm volatile("" ::: "memory"); } while (0)
; #define lane lane_id()
; template <int KB, bool SK>
; __device__ __forceinline__ void qkt(f32x16& p0, f32x16& p1, const char* K_lds, int r32, int hi, const bf16x8* qr, bool act) {
;     if (SK && !act) return;
;     p0 = f32x16{}; p1 = f32x16{};
;     const char* kb[4];
; #pragma unroll
;     for (int dd = 0; dd < 4; ++dd) kb[dd] = K_lds + KB * SHM_K + KSWZ(r32, (dd * 16 + hi * 8) * 2);
; #pragma unroll
;     for (int d0 = 0; d0 < 8; ++d0) { const char* a = kb[d0 & 3] + (d0 >> 2) * 128;
;         bf16x8 b0 = *reinterpret_cast<const bf16x8*>(a);
;         bf16x8 b1 = *reinterpret_cast<const bf16x8*>(a + 32 * 256);
;         p0 = __builtin_amdgcn_mfma_f32_32x32x16_bf16(b0, qr[d0], p0, 0, 0, 0);
;         p1 = __builtin_amdgcn_mfma_f32_32x32x16_bf16(b1, qr[d0], p1, 0, 0, 0); }
; }
; __device__ __forceinline__ void attn_block3(const BlockRef& cur, char* lds, const int wid) {
;     ...
;     A3_DMA(0);
;     A3_BAR();
;     float m_reg = -1e30f, l_reg = 0; f32x16 o[4] = {}, o2[4] = {};
;     const int vbase = (int)(uintptr_t)V_lds + v_rd_base(lane);
;     for (int t = 0; t < NT; ++t) {
;         f32x16 p0, p1; float mn, alpha; bf16x8 pa0, pa1, pa2, pa3;
;         const int kb = t * KVBLK;
;         qkt<0, false>(p0, p1, K_lds + (t & 1) * SHM_K, r32, hi, qr, true);
;         SBAR(); if (t + 1 < NT) A3_DMA(t + 1);
;         SBAR();
.LBB0_449:
	ds_read_b128 v[2:5], v252
	ds_read_b128 v[10:13], v252 offset:8192
	ds_read_b128 v[176:179], v253
	ds_read_b128 v[180:183], v253 offset:8192
	ds_read_b128 v[184:187], v254
	ds_read_b128 v[188:191], v254 offset:8192
	s_mov_b32 s6, s93
	s_waitcnt lgkmcnt(5)
	v_mfma_f32_32x32x16_bf16 v[160:175], v[2:5], v[192:195], 0
	ds_read_b128 v[2:5], v255
	s_waitcnt lgkmcnt(5)
	v_mfma_f32_32x32x16_bf16 v[144:159], v[10:13], v[192:195], 0
	ds_read_b128 v[10:13], v255 offset:8192
	s_waitcnt lgkmcnt(5)
	v_mfma_f32_32x32x16_bf16 v[160:175], v[176:179], v[196:199], v[160:175]
	ds_read_b128 v[176:179], v252 offset:128
	s_waitcnt lgkmcnt(5)
	v_mfma_f32_32x32x16_bf16 v[144:159], v[180:183], v[196:199], v[144:159]
	ds_read_b128 v[180:183], v252 offset:8320
	s_waitcnt lgkmcnt(5)
	v_mfma_f32_32x32x16_bf16 v[160:175], v[184:187], v[200:203], v[160:175]
	ds_read_b128 v[184:187], v253 offset:128
	s_waitcnt lgkmcnt(5)
	v_mfma_f32_32x32x16_bf16 v[144:159], v[188:191], v[200:203], v[144:159]
	ds_read_b128 v[188:191], v253 offset:8320
	s_waitcnt lgkmcnt(5)
	v_mfma_f32_32x32x16_bf16 v[160:175], v[2:5], v[204:207], v[160:175]
	ds_read_b128 v[2:5], v254 offset:128
	s_waitcnt lgkmcnt(5)
	v_mfma_f32_32x32x16_bf16 v[144:159], v[10:13], v[204:207], v[144:159]
	ds_read_b128 v[10:13], v254 offset:8320
	s_waitcnt lgkmcnt(5)
	v_mfma_f32_32x32x16_bf16 v[160:175], v[176:179], v[208:211], v[160:175]
	ds_read_b128 v[176:179], v255 offset:128
	s_waitcnt lgkmcnt(5)
	v_mfma_f32_32x32x16_bf16 v[144:159], v[180:183], v[208:211], v[144:159]
	ds_read_b128 v[180:183], v255 offset:8320
	s_waitcnt lgkmcnt(5)
	v_mfma_f32_32x32x16_bf16 v[160:175], v[184:187], v[212:215], v[160:175]
	s_waitcnt lgkmcnt(4)
	v_mfma_f32_32x32x16_bf16 v[144:159], v[188:191], v[212:215], v[144:159]
	s_waitcnt lgkmcnt(3)
	v_mfma_f32_32x32x16_bf16 v[160:175], v[2:5], v[216:219], v[160:175]
	s_waitcnt lgkmcnt(2)
	v_mfma_f32_32x32x16_bf16 v[144:159], v[10:13], v[216:219], v[144:159]
	s_waitcnt lgkmcnt(1)
	v_mfma_f32_32x32x16_bf16 v[160:175], v[176:179], v[220:223], v[160:175]
	s_waitcnt lgkmcnt(0)
	v_mfma_f32_32x32x16_bf16 v[144:159], v[180:183], v[220:223], v[144:159]
	s_add_i32 s93, s93, 1
	s_cmp_ge_u32 s6, s87
	s_cbranch_scc1 .Ldu451_e
	s_add_i32 m0, s83, 0x4000
	s_nop 0
	global_load_lds_dwordx4 v228, s[68:69]
	s_add_i32 m0, s82, 0x8000
	s_nop 0
	global_load_lds_dwordx4 v224, s[98:99]
	s_add_i32 m0, s82, 0xc000
	s_nop 0
	global_load_lds_dwordx4 v224, s[100:101]
	s_add_i32 m0, s83, 0x4400
	s_nop 0
	global_load_lds_dwordx4 v230, s[68:69]
	s_add_i32 m0, s82, 0x8400
	s_nop 0
	global_load_lds_dwordx4 v225, s[98:99]
	s_add_i32 m0, s82, 0xc400
	s_nop 0
	global_load_lds_dwordx4 v225, s[100:101]

; __device__ __forceinline__ void partialSM(f32x16& p0, f32x16& p1, float& m_reg, float& mn, float& alpha) {
;     ...
;     constexpr float C2 = 1.4426950408889634f * SM_SCALE;
;     if (__builtin_expect(__all((pmax - m_reg) * SM_SCALE <= THR), 1)) { mn = m_reg; alpha = 1.f; }
;     else { mn = fmaxf(m_reg, pmax); alpha = __builtin_amdgcn_exp2f((m_reg - mn) * C2); m_reg = mn; }
;     const float mnL = -mn * C2;
; #pragma unroll
;     for (int r = 0; r < 16; ++r) p0[r] = fmaf(p0[r], C2, mnL);
; #pragma unroll
;     for (int r = 0; r < 16; ++r) p1[r] = fmaf(p1[r], C2, mnL);
; #pragma unroll
;     for (int r = 0; r < 16; ++r) p0[r] = __builtin_amdgcn_exp2f(p0[r]);
; }
; __device__ __forceinline__ void finishSM(f32x16& p0, f32x16& p1, float alpha, float& l_reg, bf16x8& pa0, bf16x8& pa1, bf16x8& pa2, bf16x8& pa3) {
; #pragma unroll
;     for (int r = 0; r < 16; ++r) p1[r] = __builtin_amdgcn_exp2f(p1[r]);
;     float ps = 0;
; #pragma unroll
;     for (int r = 0; r < 16; ++r) ps += p0[r];
; #pragma unroll
;     for (int r = 0; r < 16; ++r) ps += p1[r];
;     { auto rr = __builtin_amdgcn_permlane32_swap(__float_as_uint(ps), __float_as_uint(ps), false, false);
;       ps = __uint_as_float(rr[0]) + __uint_as_float(rr[1]); }
;     l_reg = l_reg * alpha + ps;
;     PK4(p0, 0, pa0); PK4(p0, 8, pa1); PK4(p1, 0, pa2); PK4(p1, 8, pa3);
; __device__ __forceinline__ void pv_tile2(f32x16* o, f32x16* o2, int vb0, bf16x8 pa0, bf16x8 pa1, bf16x8 pa2, bf16x8 pa3) {
.Ldu_join_e:
	v_mul_f32_e32 v2, 0xbe0293ee, v249
	v_fmamk_f32 v3, v160, 0x3e0293ee, v2
	v_fmamk_f32 v4, v161, 0x3e0293ee, v2
	v_exp_f32_e32 v3, v3
	v_fmamk_f32 v5, v162, 0x3e0293ee, v2
	v_exp_f32_e32 v4, v4
	v_fmamk_f32 v6, v163, 0x3e0293ee, v2
	v_exp_f32_e32 v5, v5
	v_fmamk_f32 v7, v164, 0x3e0293ee, v2
	v_fmamk_f32 v8, v165, 0x3e0293ee, v2
	v_fmamk_f32 v9, v166, 0x3e0293ee, v2
	v_fmamk_f32 v10, v167, 0x3e0293ee, v2
	v_fmamk_f32 v11, v168, 0x3e0293ee, v2
	v_fmamk_f32 v12, v169, 0x3e0293ee, v2
	v_fmamk_f32 v13, v170, 0x3e0293ee, v2
	v_fmamk_f32 v14, v171, 0x3e0293ee, v2
	v_fmamk_f32 v15, v172, 0x3e0293ee, v2
	v_fmamk_f32 v160, v173, 0x3e0293ee, v2
	v_fmamk_f32 v161, v174, 0x3e0293ee, v2
	v_fmamk_f32 v162, v175, 0x3e0293ee, v2
	v_fmamk_f32 v144, v144, 0x3e0293ee, v2
	v_fmamk_f32 v145, v145, 0x3e0293ee, v2
	v_fmamk_f32 v146, v146, 0x3e0293ee, v2
	v_fmamk_f32 v147, v147, 0x3e0293ee, v2
	v_fmamk_f32 v148, v148, 0x3e0293ee, v2
	v_fmamk_f32 v149, v149, 0x3e0293ee, v2
	v_fmamk_f32 v150, v150, 0x3e0293ee, v2
	v_fmamk_f32 v151, v151, 0x3e0293ee, v2
	v_fmamk_f32 v152, v152, 0x3e0293ee, v2
	v_fmamk_f32 v153, v153, 0x3e0293ee, v2
	v_fmamk_f32 v154, v154, 0x3e0293ee, v2
	v_fmamk_f32 v155, v155, 0x3e0293ee, v2
	v_fmamk_f32 v156, v156, 0x3e0293ee, v2
	v_fmamk_f32 v157, v157, 0x3e0293ee, v2
	v_fmamk_f32 v158, v158, 0x3e0293ee, v2
	v_fmac_f32_e32 v2, 0x3e0293ee, v159
	v_exp_f32_e32 v159, v6
	v_exp_f32_e32 v163, v7
	v_exp_f32_e32 v165, v2
	v_add_f32_e32 v2, 0, v3
	v_exp_f32_e32 v8, v8
	v_add_f32_e32 v2, v4, v2
	v_exp_f32_e32 v9, v9
	v_add_f32_e32 v2, v5, v2
	v_exp_f32_e32 v10, v10
	v_add_f32_e32 v2, v159, v2
	v_exp_f32_e32 v11, v11
	v_add_f32_e32 v2, v163, v2
	v_exp_f32_e32 v12, v12
	v_add_f32_e32 v2, v8, v2
	v_exp_f32_e32 v13, v13
	v_add_f32_e32 v2, v9, v2
	v_exp_f32_e32 v164, v14
	v_add_f32_e32 v2, v10, v2
	v_exp_f32_e32 v15, v15
	v_add_f32_e32 v2, v11, v2
	v_exp_f32_e32 v160, v160
	v_add_f32_e32 v2, v12, v2
	v_exp_f32_e32 v161, v161
	v_add_f32_e32 v2, v13, v2
	v_exp_f32_e32 v162, v162
	v_add_f32_e32 v2, v164, v2
	v_exp_f32_e32 v144, v144
	v_add_f32_e32 v2, v15, v2
	v_exp_f32_e32 v145, v145
	v_add_f32_e32 v2, v160, v2
	v_exp_f32_e32 v146, v146
	v_add_f32_e32 v2, v161, v2
	v_exp_f32_e32 v147, v147
	v_add_f32_e32 v2, v162, v2
	v_exp_f32_e32 v148, v148
	v_add_f32_e32 v2, v144, v2
	v_exp_f32_e32 v149, v149
	v_add_f32_e32 v2, v145, v2
	v_exp_f32_e32 v150, v150
	v_add_f32_e32 v2, v146, v2
	v_exp_f32_e32 v151, v151
	v_add_f32_e32 v2, v147, v2
	v_exp_f32_e32 v152, v152
	v_add_f32_e32 v2, v148, v2
	v_exp_f32_e32 v153, v153
	v_add_f32_e32 v2, v149, v2
	v_exp_f32_e32 v154, v154
	v_add_f32_e32 v2, v150, v2
	v_exp_f32_e32 v155, v155
	v_add_f32_e32 v2, v151, v2
	v_exp_f32_e32 v156, v156
	v_add_f32_e32 v2, v152, v2
	v_exp_f32_e32 v157, v157
	v_add_f32_e32 v2, v153, v2
	v_exp_f32_e32 v158, v158
	v_add_f32_e32 v2, v154, v2
	v_add_f32_e32 v2, v155, v2
	v_add_f32_e32 v2, v156, v2
	v_add_f32_e32 v2, v157, v2
	v_add_f32_e32 v2, v158, v2
	v_add_f32_e32 v2, v165, v2
	v_mov_b32_e32 v6, v2
	s_nop 1
	v_permlane32_swap_b32_e32 v2, v6
	v_add_f32_e32 v14, v2, v6
	v_fma_f32 v250, v250, v0, v14
	v_cvt_pk_bf16_f32 v6, v3, v4
	v_cvt_pk_bf16_f32 v7, v5, v159
	v_cvt_pk_bf16_f32 v8, v163, v8
	v_cvt_pk_bf16_f32 v9, v9, v10
	v_cvt_pk_bf16_f32 v10, v11, v12
	v_cvt_pk_bf16_f32 v11, v13, v164
	v_cvt_pk_bf16_f32 v12, v15, v160
	v_cvt_pk_bf16_f32 v13, v161, v162
	v_cvt_pk_bf16_f32 v144, v144, v145
	v_cvt_pk_bf16_f32 v145, v146, v147
	v_cvt_pk_bf16_f32 v146, v148, v149
	v_cvt_pk_bf16_f32 v147, v150, v151
	v_cvt_pk_bf16_f32 v2, v152, v153
	v_cvt_pk_bf16_f32 v3, v154, v155
	v_cvt_pk_bf16_f32 v4, v156, v157
	v_cvt_pk_bf16_f32 v5, v158, v165
	s_nop 0
	v_permlane32_swap_b32_e32 v6, v8
	v_permlane32_swap_b32_e32 v7, v9
	v_permlane32_swap_b32_e32 v10, v12
	v_permlane32_swap_b32_e32 v11, v13
	v_permlane32_swap_b32_e32 v144, v146
	v_permlane32_swap_b32_e32 v145, v147
	v_permlane32_swap_b32_e32 v2, v4
	v_permlane32_swap_b32_e32 v3, v5
	ds_read_b64_tr_b16 v[148:149], v246 offset:0x0
	ds_read_b64_tr_b16 v[150:151], v246 offset:0x800
	ds_read_b64_tr_b16 v[152:153], v246 offset:0x4000
	ds_read_b64_tr_b16 v[154:155], v246 offset:0x4800
	ds_read_b64_tr_b16 v[156:157], v246 offset:0x1000
	ds_read_b64_tr_b16 v[158:159], v246 offset:0x1800
	ds_read_b64_tr_b16 v[160:161], v246 offset:0x5000
	ds_read_b64_tr_b16 v[162:163], v246 offset:0x5800
	ds_read_b64_tr_b16 v[164:165], v246 offset:0x2000
	ds_read_b64_tr_b16 v[166:167], v246 offset:0x2800
	ds_read_b64_tr_b16 v[168:169], v246 offset:0x6000
	ds_read_b64_tr_b16 v[170:171], v246 offset:0x6800
	ds_read_b64_tr_b16 v[172:173], v246 offset:0x3000
	ds_read_b64_tr_b16 v[174:175], v246 offset:0x3800
	ds_read_b64_tr_b16 v[176:177], v246 offset:0x7000
	ds_read_b64_tr_b16 v[178:179], v246 offset:0x7800
	s_waitcnt lgkmcnt(0)
; #define A3_BAR() do { asm volatile("s_waitcnt vmcnt(0) lgkmcnt(0)" ::: "memory"); __builtin_amdgcn_s_barrier(); asm volatile("" ::: "memory"); } while (0)
; __device__ __forceinline__ void pv_tile2(f32x16* o, f32x16* o2, int vb0, bf16x8 pa0, bf16x8 pa1, bf16x8 pa2, bf16x8 pa3) {
;     ...
;     PV2_D0(0); PV2_D0(1); PV2_D0(2); PV2_D0(3);
; __device__ __forceinline__ void attn_block3(const BlockRef& cur, char* lds, const int wid) {
;     ...
;         pv_tile2(o, o2, vbase + (t & 1) * 2 * SHM_V, pa0, pa1, pa2, pa3);
;         A3_BAR();
	s_nop 0
	v_mfma_f32_32x32x16_bf16 v[112:127], v[6:9], v[148:151], v[112:127]
	ds_read_b64_tr_b16 v[148:149], v246 offset:0x200
	ds_read_b64_tr_b16 v[150:151], v246 offset:0xa00
	v_mfma_f32_32x32x16_bf16 v[128:143], v[6:9], v[152:155], v[128:143]
	ds_read_b64_tr_b16 v[152:153], v246 offset:0x4200
	ds_read_b64_tr_b16 v[154:155], v246 offset:0x4a00
	v_mfma_f32_32x32x16_bf16 v[112:127], v[10:13], v[156:159], v[112:127]
	ds_read_b64_tr_b16 v[156:157], v246 offset:0x1200
	ds_read_b64_tr_b16 v[158:159], v246 offset:0x1a00
	v_mfma_f32_32x32x16_bf16 v[128:143], v[10:13], v[160:163], v[128:143]
	ds_read_b64_tr_b16 v[160:161], v246 offset:0x5200
	ds_read_b64_tr_b16 v[162:163], v246 offset:0x5a00
	v_mfma_f32_32x32x16_bf16 v[112:127], v[144:147], v[164:167], v[112:127]
	ds_read_b64_tr_b16 v[164:165], v246 offset:0x2200
	ds_read_b64_tr_b16 v[166:167], v246 offset:0x2a00
	v_mfma_f32_32x32x16_bf16 v[128:143], v[144:147], v[168:171], v[128:143]
	ds_read_b64_tr_b16 v[168:169], v246 offset:0x6200
	ds_read_b64_tr_b16 v[170:171], v246 offset:0x6a00
	v_mfma_f32_32x32x16_bf16 v[112:127], v[2:5], v[172:175], v[112:127]
	ds_read_b64_tr_b16 v[172:173], v246 offset:0x3200
	ds_read_b64_tr_b16 v[174:175], v246 offset:0x3a00
	v_mfma_f32_32x32x16_bf16 v[128:143], v[2:5], v[176:179], v[128:143]
	ds_read_b64_tr_b16 v[176:177], v246 offset:0x7200
	ds_read_b64_tr_b16 v[178:179], v246 offset:0x7a00
	s_waitcnt lgkmcnt(0)
	v_mfma_f32_32x32x16_bf16 v[80:95], v[6:9], v[148:151], v[80:95]
	ds_read_b64_tr_b16 v[148:149], v246 offset:0x400
	ds_read_b64_tr_b16 v[150:151], v246 offset:0xc00
	v_mfma_f32_32x32x16_bf16 v[96:111], v[6:9], v[152:155], v[96:111]
	ds_read_b64_tr_b16 v[152:153], v246 offset:0x4400
	ds_read_b64_tr_b16 v[154:155], v246 offset:0x4c00
	v_mfma_f32_32x32x16_bf16 v[80:95], v[10:13], v[156:159], v[80:95]
	ds_read_b64_tr_b16 v[156:157], v246 offset:0x1400
	ds_read_b64_tr_b16 v[158:159], v246 offset:0x1c00
	v_mfma_f32_32x32x16_bf16 v[96:111], v[10:13], v[160:163], v[96:111]
	ds_read_b64_tr_b16 v[160:161], v246 offset:0x5400
	ds_read_b64_tr_b16 v[162:163], v246 offset:0x5c00
	v_mfma_f32_32x32x16_bf16 v[80:95], v[144:147], v[164:167], v[80:95]
	ds_read_b64_tr_b16 v[164:165], v246 offset:0x2400
	ds_read_b64_tr_b16 v[166:167], v246 offset:0x2c00
	v_mfma_f32_32x32x16_bf16 v[96:111], v[144:147], v[168:171], v[96:111]
	ds_read_b64_tr_b16 v[168:169], v246 offset:0x6400
	ds_read_b64_tr_b16 v[170:171], v246 offset:0x6c00
	v_mfma_f32_32x32x16_bf16 v[80:95], v[2:5], v[172:175], v[80:95]
	ds_read_b64_tr_b16 v[172:173], v246 offset:0x3400
	ds_read_b64_tr_b16 v[174:175], v246 offset:0x3c00
	v_mfma_f32_32x32x16_bf16 v[96:111], v[2:5], v[176:179], v[96:111]
	ds_read_b64_tr_b16 v[176:177], v246 offset:0x7400
	ds_read_b64_tr_b16 v[178:179], v246 offset:0x7c00
	s_waitcnt lgkmcnt(0)
	v_mfma_f32_32x32x16_bf16 v[48:63], v[6:9], v[148:151], v[48:63]
	ds_read_b64_tr_b16 v[148:149], v246 offset:0x600
	ds_read_b64_tr_b16 v[150:151], v246 offset:0xe00
	v_mfma_f32_32x32x16_bf16 v[64:79], v[6:9], v[152:155], v[64:79]
	ds_read_b64_tr_b16 v[152:153], v246 offset:0x4600
	ds_read_b64_tr_b16 v[154:155], v246 offset:0x4e00
	v_mfma_f32_32x32x16_bf16 v[48:63], v[10:13], v[156:159], v[48:63]
	ds_read_b64_tr_b16 v[156:157], v246 offset:0x1600
	ds_read_b64_tr_b16 v[158:159], v246 offset:0x1e00
	v_mfma_f32_32x32x16_bf16 v[64:79], v[10:13], v[160:163], v[64:79]
	ds_read_b64_tr_b16 v[160:161], v246 offset:0x5600
	ds_read_b64_tr_b16 v[162:163], v246 offset:0x5e00
	v_mfma_f32_32x32x16_bf16 v[48:63], v[144:147], v[164:167], v[48:63]
	ds_read_b64_tr_b16 v[164:165], v246 offset:0x2600
	ds_read_b64_tr_b16 v[166:167], v246 offset:0x2e00
	v_mfma_f32_32x32x16_bf16 v[64:79], v[144:147], v[168:171], v[64:79]
	ds_read_b64_tr_b16 v[168:169], v246 offset:0x6600
	ds_read_b64_tr_b16 v[170:171], v246 offset:0x6e00
	v_mfma_f32_32x32x16_bf16 v[48:63], v[2:5], v[172:175], v[48:63]
	ds_read_b64_tr_b16 v[172:173], v246 offset:0x3600
	ds_read_b64_tr_b16 v[174:175], v246 offset:0x3e00
	v_mfma_f32_32x32x16_bf16 v[64:79], v[2:5], v[176:179], v[64:79]
	ds_read_b64_tr_b16 v[176:177], v246 offset:0x7600
	ds_read_b64_tr_b16 v[178:179], v246 offset:0x7e00
	s_waitcnt lgkmcnt(0)
	v_mfma_f32_32x32x16_bf16 v[16:31], v[6:9], v[148:151], v[16:31]
	s_waitcnt vmcnt(0) lgkmcnt(0)
	s_barrier
	s_add_u32 s68, s68, 0x4000
	s_addc_u32 s69, s69, 0
	s_add_u32 s98, s98, 0x4000
	s_addc_u32 s99, s99, 0
	s_add_u32 s100, s100, 0x4000
	s_addc_u32 s101, s101, 0
	s_add_i32 s90, s90, 64
	v_add_u32_e32 v247, 0xffffff00, v247
	v_mfma_f32_32x32x16_bf16 v[32:47], v[6:9], v[152:155], v[32:47]
	v_subrev_u32_e32 v248, 64, v248
	s_cmp_eq_u32 s88, s93
	v_mfma_f32_32x32x16_bf16 v[16:31], v[10:13], v[156:159], v[16:31]
	v_mfma_f32_32x32x16_bf16 v[32:47], v[10:13], v[160:163], v[32:47]
	v_mfma_f32_32x32x16_bf16 v[16:31], v[144:147], v[164:167], v[16:31]
	v_mfma_f32_32x32x16_bf16 v[32:47], v[144:147], v[168:171], v[32:47]
	v_mfma_f32_32x32x16_bf16 v[16:31], v[2:5], v[172:175], v[16:31]
	v_mfma_f32_32x32x16_bf16 v[32:47], v[2:5], v[176:179], v[32:47]
	s_cbranch_scc1 .LBB0_491
	s_branch .Ldu_odd

; #define SBAR() __builtin_amdgcn_sched_barrier(0)
; __device__ __forceinline__ int v_rd_base(int lane) { return ((lane & 3) << 3) | (((lane >> 2) & 3) << 6) | (((lane >> 4) & 1) << 5) | (((lane >> 5) & 1) << 8); }
; #define A3_BAR() do { asm volatile("s_waitcnt vmcnt(0) lgkmcnt(0)" ::: "memory"); __builtin_amdgcn_s_barrier(); asm volatile("" ::: "memory"); } while (0)
; #define lane lane_id()
; template <int KB, bool SK>
; __device__ __forceinline__ void qkt(f32x16& p0, f32x16& p1, const char* K_lds, int r32, int hi, const bf16x8* qr, bool act) {
;     if (SK && !act) return;
;     p0 = f32x16{}; p1 = f32x16{};
;     const char* kb[4];
; #pragma unroll
;     for (int dd = 0; dd < 4; ++dd) kb[dd] = K_lds + KB * SHM_K + KSWZ(r32, (dd * 16 + hi * 8) * 2);
; #pragma unroll
;     for (int d0 = 0; d0 < 8; ++d0) { const char* a = kb[d0 & 3] + (d0 >> 2) * 128;
;         bf16x8 b0 = *reinterpret_cast<const bf16x8*>(a);
;         bf16x8 b1 = *reinterpret_cast<const bf16x8*>(a + 32 * 256);
;         p0 = __builtin_amdgcn_mfma_f32_32x32x16_bf16(b0, qr[d0], p0, 0, 0, 0);
;         p1 = __builtin_amdgcn_mfma_f32_32x32x16_bf16(b1, qr[d0], p1, 0, 0, 0); }
; }
; __device__ __forceinline__ void attn_block3(const BlockRef& cur, char* lds, const int wid) {
;     ...
;     A3_DMA(0);
;     A3_BAR();
;     float m_reg = -1e30f, l_reg = 0; f32x16 o[4] = {}, o2[4] = {};
;     const int vbase = (int)(uintptr_t)V_lds + v_rd_base(lane);
;     for (int t = 0; t < NT; ++t) {
;         f32x16 p0, p1; float mn, alpha; bf16x8 pa0, pa1, pa2, pa3;
;         const int kb = t * KVBLK;
;         qkt<0, false>(p0, p1, K_lds + (t & 1) * SHM_K, r32, hi, qr, true);
;         SBAR(); if (t + 1 < NT) A3_DMA(t + 1);
;         SBAR();
.Ldu_odd:
	ds_read_b128 v[2:5], v252 offset:16384
	ds_read_b128 v[10:13], v252 offset:24576
	ds_read_b128 v[176:179], v253 offset:16384
	ds_read_b128 v[180:183], v253 offset:24576
	ds_read_b128 v[184:187], v254 offset:16384
	ds_read_b128 v[188:191], v254 offset:24576
	s_mov_b32 s6, s93
	s_waitcnt lgkmcnt(5)
	v_mfma_f32_32x32x16_bf16 v[160:175], v[2:5], v[192:195], 0
	ds_read_b128 v[2:5], v255 offset:16384
	s_waitcnt lgkmcnt(5)
	v_mfma_f32_32x32x16_bf16 v[144:159], v[10:13], v[192:195], 0
	ds_read_b128 v[10:13], v255 offset:24576
	s_waitcnt lgkmcnt(5)
	v_mfma_f32_32x32x16_bf16 v[160:175], v[176:179], v[196:199], v[160:175]
	ds_read_b128 v[176:179], v252 offset:16512
	s_waitcnt lgkmcnt(5)
	v_mfma_f32_32x32x16_bf16 v[144:159], v[180:183], v[196:199], v[144:159]
	ds_read_b128 v[180:183], v252 offset:24704
	s_waitcnt lgkmcnt(5)
	v_mfma_f32_32x32x16_bf16 v[160:175], v[184:187], v[200:203], v[160:175]
	ds_read_b128 v[184:187], v253 offset:16512
	s_waitcnt lgkmcnt(5)
	v_mfma_f32_32x32x16_bf16 v[144:159], v[188:191], v[200:203], v[144:159]
	ds_read_b128 v[188:191], v253 offset:24704
	s_waitcnt lgkmcnt(5)
	v_mfma_f32_32x32x16_bf16 v[160:175], v[2:5], v[204:207], v[160:175]
	ds_read_b128 v[2:5], v254 offset:16512
	s_waitcnt lgkmcnt(5)
	v_mfma_f32_32x32x16_bf16 v[144:159], v[10:13], v[204:207], v[144:159]
	ds_read_b128 v[10:13], v254 offset:24704
	s_waitcnt lgkmcnt(5)
	v_mfma_f32_32x32x16_bf16 v[160:175], v[176:179], v[208:211], v[160:175]
	ds_read_b128 v[176:179], v255 offset:16512
	s_waitcnt lgkmcnt(5)
	v_mfma_f32_32x32x16_bf16 v[144:159], v[180:183], v[208:211], v[144:159]
	ds_read_b128 v[180:183], v255 offset:24704
	s_waitcnt lgkmcnt(5)
	v_mfma_f32_32x32x16_bf16 v[160:175], v[184:187], v[212:215], v[160:175]
	s_waitcnt lgkmcnt(4)
	v_mfma_f32_32x32x16_bf16 v[144:159], v[188:191], v[212:215], v[144:159]
	s_waitcnt lgkmcnt(3)
	v_mfma_f32_32x32x16_bf16 v[160:175], v[2:5], v[216:219], v[160:175]
	s_waitcnt lgkmcnt(2)
	v_mfma_f32_32x32x16_bf16 v[144:159], v[10:13], v[216:219], v[144:159]
	s_waitcnt lgkmcnt(1)
	v_mfma_f32_32x32x16_bf16 v[160:175], v[176:179], v[220:223], v[160:175]
	s_waitcnt lgkmcnt(0)
	v_mfma_f32_32x32x16_bf16 v[144:159], v[180:183], v[220:223], v[144:159]
	s_add_i32 s93, s93, 1
	s_cmp_ge_u32 s6, s87
	s_cbranch_scc1 .Ldu451_o
	s_mov_b32 m0, s83
	s_nop 0
	global_load_lds_dwordx4 v228, s[68:69]
	s_mov_b32 m0, s82
	s_nop 0
	global_load_lds_dwordx4 v224, s[98:99]
	s_add_i32 m0, s82, 0x4000
	s_nop 0
	global_load_lds_dwordx4 v224, s[100:101]
	s_add_i32 m0, s83, 0x400
	s_nop 0
	global_load_lds_dwordx4 v230, s[68:69]
	s_add_i32 m0, s82, 0x400
	s_nop 0
	global_load_lds_dwordx4 v225, s[98:99]
	s_add_i32 m0, s82, 0x4400
	s_nop 0
	global_load_lds_dwordx4 v225, s[100:101]

; __device__ __forceinline__ void partialSM(f32x16& p0, f32x16& p1, float& m_reg, float& mn, float& alpha) {
;     ...
;     constexpr float C2 = 1.4426950408889634f * SM_SCALE;
;     if (__builtin_expect(__all((pmax - m_reg) * SM_SCALE <= THR), 1)) { mn = m_reg; alpha = 1.f; }
;     else { mn = fmaxf(m_reg, pmax); alpha = __builtin_amdgcn_exp2f((m_reg - mn) * C2); m_reg = mn; }
;     const float mnL = -mn * C2;
; #pragma unroll
;     for (int r = 0; r < 16; ++r) p0[r] = fmaf(p0[r], C2, mnL);
; #pragma unroll
;     for (int r = 0; r < 16; ++r) p1[r] = fmaf(p1[r], C2, mnL);
; #pragma unroll
;     for (int r = 0; r < 16; ++r) p0[r] = __builtin_amdgcn_exp2f(p0[r]);
; }
; __device__ __forceinline__ void finishSM(f32x16& p0, f32x16& p1, float alpha, float& l_reg, bf16x8& pa0, bf16x8& pa1, bf16x8& pa2, bf16x8& pa3) {
; #pragma unroll
;     for (int r = 0; r < 16; ++r) p1[r] = __builtin_amdgcn_exp2f(p1[r]);
;     float ps = 0;
; #pragma unroll
;     for (int r = 0; r < 16; ++r) ps += p0[r];
; #pragma unroll
;     for (int r = 0; r < 16; ++r) ps += p1[r];
;     { auto rr = __builtin_amdgcn_permlane32_swap(__float_as_uint(ps), __float_as_uint(ps), false, false);
;       ps = __uint_as_float(rr[0]) + __uint_as_float(rr[1]); }
;     l_reg = l_reg * alpha + ps;
;     PK4(p0, 0, pa0); PK4(p0, 8, pa1); PK4(p1, 0, pa2); PK4(p1, 8, pa3);
; __device__ __forceinline__ void pv_tile2(f32x16* o, f32x16* o2, int vb0, bf16x8 pa0, bf16x8 pa1, bf16x8 pa2, bf16x8 pa3) {
.Ldu_join_o:
	v_mul_f32_e32 v2, 0xbe0293ee, v249
	v_fmamk_f32 v3, v160, 0x3e0293ee, v2
	v_fmamk_f32 v4, v161, 0x3e0293ee, v2
	v_exp_f32_e32 v3, v3
	v_fmamk_f32 v5, v162, 0x3e0293ee, v2
	v_exp_f32_e32 v4, v4
	v_fmamk_f32 v6, v163, 0x3e0293ee, v2
	v_exp_f32_e32 v5, v5
	v_fmamk_f32 v7, v164, 0x3e0293ee, v2
	v_fmamk_f32 v8, v165, 0x3e0293ee, v2
	v_fmamk_f32 v9, v166, 0x3e0293ee, v2
	v_fmamk_f32 v10, v167, 0x3e0293ee, v2
	v_fmamk_f32 v11, v168, 0x3e0293ee, v2
	v_fmamk_f32 v12, v169, 0x3e0293ee, v2
	v_fmamk_f32 v13, v170, 0x3e0293ee, v2
	v_fmamk_f32 v14, v171, 0x3e0293ee, v2
	v_fmamk_f32 v15, v172, 0x3e0293ee, v2
	v_fmamk_f32 v160, v173, 0x3e0293ee, v2
	v_fmamk_f32 v161, v174, 0x3e0293ee, v2
	v_fmamk_f32 v162, v175, 0x3e0293ee, v2
	v_fmamk_f32 v144, v144, 0x3e0293ee, v2
	v_fmamk_f32 v145, v145, 0x3e0293ee, v2
	v_fmamk_f32 v146, v146, 0x3e0293ee, v2
	v_fmamk_f32 v147, v147, 0x3e0293ee, v2
	v_fmamk_f32 v148, v148, 0x3e0293ee, v2
	v_fmamk_f32 v149, v149, 0x3e0293ee, v2
	v_fmamk_f32 v150, v150, 0x3e0293ee, v2
	v_fmamk_f32 v151, v151, 0x3e0293ee, v2
	v_fmamk_f32 v152, v152, 0x3e0293ee, v2
	v_fmamk_f32 v153, v153, 0x3e0293ee, v2
	v_fmamk_f32 v154, v154, 0x3e0293ee, v2
	v_fmamk_f32 v155, v155, 0x3e0293ee, v2
	v_fmamk_f32 v156, v156, 0x3e0293ee, v2
	v_fmamk_f32 v157, v157, 0x3e0293ee, v2
	v_fmamk_f32 v158, v158, 0x3e0293ee, v2
	v_fmac_f32_e32 v2, 0x3e0293ee, v159
	v_exp_f32_e32 v159, v6
	v_exp_f32_e32 v163, v7
	v_exp_f32_e32 v165, v2
	v_add_f32_e32 v2, 0, v3
	v_exp_f32_e32 v8, v8
	v_add_f32_e32 v2, v4, v2
	v_exp_f32_e32 v9, v9
	v_add_f32_e32 v2, v5, v2
	v_exp_f32_e32 v10, v10
	v_add_f32_e32 v2, v159, v2
	v_exp_f32_e32 v11, v11
	v_add_f32_e32 v2, v163, v2
	v_exp_f32_e32 v12, v12
	v_add_f32_e32 v2, v8, v2
	v_exp_f32_e32 v13, v13
	v_add_f32_e32 v2, v9, v2
	v_exp_f32_e32 v164, v14
	v_add_f32_e32 v2, v10, v2
	v_exp_f32_e32 v15, v15
	v_add_f32_e32 v2, v11, v2
	v_exp_f32_e32 v160, v160
	v_add_f32_e32 v2, v12, v2
	v_exp_f32_e32 v161, v161
	v_add_f32_e32 v2, v13, v2
	v_exp_f32_e32 v162, v162
	v_add_f32_e32 v2, v164, v2
	v_exp_f32_e32 v144, v144
	v_add_f32_e32 v2, v15, v2
	v_exp_f32_e32 v145, v145
	v_add_f32_e32 v2, v160, v2
	v_exp_f32_e32 v146, v146
	v_add_f32_e32 v2, v161, v2
	v_exp_f32_e32 v147, v147
	v_add_f32_e32 v2, v162, v2
	v_exp_f32_e32 v148, v148
	v_add_f32_e32 v2, v144, v2
	v_exp_f32_e32 v149, v149
	v_add_f32_e32 v2, v145, v2
	v_exp_f32_e32 v150, v150
	v_add_f32_e32 v2, v146, v2
	v_exp_f32_e32 v151, v151
	v_add_f32_e32 v2, v147, v2
	v_exp_f32_e32 v152, v152
	v_add_f32_e32 v2, v148, v2
	v_exp_f32_e32 v153, v153
	v_add_f32_e32 v2, v149, v2
	v_exp_f32_e32 v154, v154
	v_add_f32_e32 v2, v150, v2
	v_exp_f32_e32 v155, v155
	v_add_f32_e32 v2, v151, v2
	v_exp_f32_e32 v156, v156
	v_add_f32_e32 v2, v152, v2
	v_exp_f32_e32 v157, v157
	v_add_f32_e32 v2, v153, v2
	v_exp_f32_e32 v158, v158
	v_add_f32_e32 v2, v154, v2
	v_add_f32_e32 v2, v155, v2
	v_add_f32_e32 v2, v156, v2
	v_add_f32_e32 v2, v157, v2
	v_add_f32_e32 v2, v158, v2
	v_add_f32_e32 v2, v165, v2
	v_mov_b32_e32 v6, v2
	s_nop 1
	v_permlane32_swap_b32_e32 v2, v6
	v_add_f32_e32 v14, v2, v6
	v_fma_f32 v250, v250, v0, v14
	v_cvt_pk_bf16_f32 v6, v3, v4
	v_cvt_pk_bf16_f32 v7, v5, v159
	v_cvt_pk_bf16_f32 v8, v163, v8
	v_cvt_pk_bf16_f32 v9, v9, v10
	v_cvt_pk_bf16_f32 v10, v11, v12
	v_cvt_pk_bf16_f32 v11, v13, v164
	v_cvt_pk_bf16_f32 v12, v15, v160
	v_cvt_pk_bf16_f32 v13, v161, v162
	v_cvt_pk_bf16_f32 v144, v144, v145
	v_cvt_pk_bf16_f32 v145, v146, v147
	v_cvt_pk_bf16_f32 v146, v148, v149
	v_cvt_pk_bf16_f32 v147, v150, v151
	v_cvt_pk_bf16_f32 v2, v152, v153
	v_cvt_pk_bf16_f32 v3, v154, v155
	v_cvt_pk_bf16_f32 v4, v156, v157
	v_cvt_pk_bf16_f32 v5, v158, v165
	s_nop 0
	v_permlane32_swap_b32_e32 v6, v8
	v_permlane32_swap_b32_e32 v7, v9
	v_permlane32_swap_b32_e32 v10, v12
	v_permlane32_swap_b32_e32 v11, v13
	v_permlane32_swap_b32_e32 v144, v146
	v_permlane32_swap_b32_e32 v145, v147
	v_permlane32_swap_b32_e32 v2, v4
	v_permlane32_swap_b32_e32 v3, v5
	ds_read_b64_tr_b16 v[148:149], v246 offset:0x8000
	ds_read_b64_tr_b16 v[150:151], v246 offset:0x8800
	ds_read_b64_tr_b16 v[152:153], v246 offset:0xc000
	ds_read_b64_tr_b16 v[154:155], v246 offset:0xc800
	ds_read_b64_tr_b16 v[156:157], v246 offset:0x9000
	ds_read_b64_tr_b16 v[158:159], v246 offset:0x9800
	ds_read_b64_tr_b16 v[160:161], v246 offset:0xd000
	ds_read_b64_tr_b16 v[162:163], v246 offset:0xd800
	ds_read_b64_tr_b16 v[164:165], v246 offset:0xa000
	ds_read_b64_tr_b16 v[166:167], v246 offset:0xa800
	ds_read_b64_tr_b16 v[168:169], v246 offset:0xe000
	ds_read_b64_tr_b16 v[170:171], v246 offset:0xe800
	ds_read_b64_tr_b16 v[172:173], v246 offset:0xb000
	ds_read_b64_tr_b16 v[174:175], v246 offset:0xb800
	ds_read_b64_tr_b16 v[176:177], v246 offset:0xf000
	ds_read_b64_tr_b16 v[178:179], v246 offset:0xf800
	s_waitcnt lgkmcnt(0)
; #define A3_BAR() do { asm volatile("s_waitcnt vmcnt(0) lgkmcnt(0)" ::: "memory"); __builtin_amdgcn_s_barrier(); asm volatile("" ::: "memory"); } while (0)
; __device__ __forceinline__ void pv_tile2(f32x16* o, f32x16* o2, int vb0, bf16x8 pa0, bf16x8 pa1, bf16x8 pa2, bf16x8 pa3) {
;     ...
;     PV2_D0(0); PV2_D0(1); PV2_D0(2); PV2_D0(3);
; __device__ __forceinline__ void attn_block3(const BlockRef& cur, char* lds, const int wid) {
;     ...
;         pv_tile2(o, o2, vbase + (t & 1) * 2 * SHM_V, pa0, pa1, pa2, pa3);
;         A3_BAR();
	s_nop 0
	v_mfma_f32_32x32x16_bf16 v[112:127], v[6:9], v[148:151], v[112:127]
	ds_read_b64_tr_b16 v[148:149], v246 offset:0x8200
	ds_read_b64_tr_b16 v[150:151], v246 offset:0x8a00
	v_mfma_f32_32x32x16_bf16 v[128:143], v[6:9], v[152:155], v[128:143]
	ds_read_b64_tr_b16 v[152:153], v246 offset:0xc200
	ds_read_b64_tr_b16 v[154:155], v246 offset:0xca00
	v_mfma_f32_32x32x16_bf16 v[112:127], v[10:13], v[156:159], v[112:127]
	ds_read_b64_tr_b16 v[156:157], v246 offset:0x9200
	ds_read_b64_tr_b16 v[158:159], v246 offset:0x9a00
	v_mfma_f32_32x32x16_bf16 v[128:143], v[10:13], v[160:163], v[128:143]
	ds_read_b64_tr_b16 v[160:161], v246 offset:0xd200
	ds_read_b64_tr_b16 v[162:163], v246 offset:0xda00
	v_mfma_f32_32x32x16_bf16 v[112:127], v[144:147], v[164:167], v[112:127]
	ds_read_b64_tr_b16 v[164:165], v246 offset:0xa200
	ds_read_b64_tr_b16 v[166:167], v246 offset:0xaa00
	v_mfma_f32_32x32x16_bf16 v[128:143], v[144:147], v[168:171], v[128:143]
	ds_read_b64_tr_b16 v[168:169], v246 offset:0xe200
	ds_read_b64_tr_b16 v[170:171], v246 offset:0xea00
	v_mfma_f32_32x32x16_bf16 v[112:127], v[2:5], v[172:175], v[112:127]
	ds_read_b64_tr_b16 v[172:173], v246 offset:0xb200
	ds_read_b64_tr_b16 v[174:175], v246 offset:0xba00
	v_mfma_f32_32x32x16_bf16 v[128:143], v[2:5], v[176:179], v[128:143]
	ds_read_b64_tr_b16 v[176:177], v246 offset:0xf200
	ds_read_b64_tr_b16 v[178:179], v246 offset:0xfa00
	s_waitcnt lgkmcnt(0)
	v_mfma_f32_32x32x16_bf16 v[80:95], v[6:9], v[148:151], v[80:95]
	ds_read_b64_tr_b16 v[148:149], v246 offset:0x8400
	ds_read_b64_tr_b16 v[150:151], v246 offset:0x8c00
	v_mfma_f32_32x32x16_bf16 v[96:111], v[6:9], v[152:155], v[96:111]
	ds_read_b64_tr_b16 v[152:153], v246 offset:0xc400
	ds_read_b64_tr_b16 v[154:155], v246 offset:0xcc00
	v_mfma_f32_32x32x16_bf16 v[80:95], v[10:13], v[156:159], v[80:95]
	ds_read_b64_tr_b16 v[156:157], v246 offset:0x9400
	ds_read_b64_tr_b16 v[158:159], v246 offset:0x9c00
	v_mfma_f32_32x32x16_bf16 v[96:111], v[10:13], v[160:163], v[96:111]
	ds_read_b64_tr_b16 v[160:161], v246 offset:0xd400
	ds_read_b64_tr_b16 v[162:163], v246 offset:0xdc00
	v_mfma_f32_32x32x16_bf16 v[80:95], v[144:147], v[164:167], v[80:95]
	ds_read_b64_tr_b16 v[164:165], v246 offset:0xa400
	ds_read_b64_tr_b16 v[166:167], v246 offset:0xac00
	v_mfma_f32_32x32x16_bf16 v[96:111], v[144:147], v[168:171], v[96:111]
	ds_read_b64_tr_b16 v[168:169], v246 offset:0xe400
	ds_read_b64_tr_b16 v[170:171], v246 offset:0xec00
	v_mfma_f32_32x32x16_bf16 v[80:95], v[2:5], v[172:175], v[80:95]
	ds_read_b64_tr_b16 v[172:173], v246 offset:0xb400
	ds_read_b64_tr_b16 v[174:175], v246 offset:0xbc00
	v_mfma_f32_32x32x16_bf16 v[96:111], v[2:5], v[176:179], v[96:111]
	ds_read_b64_tr_b16 v[176:177], v246 offset:0xf400
	ds_read_b64_tr_b16 v[178:179], v246 offset:0xfc00
	s_waitcnt lgkmcnt(0)
	v_mfma_f32_32x32x16_bf16 v[48:63], v[6:9], v[148:151], v[48:63]
	ds_read_b64_tr_b16 v[148:149], v246 offset:0x8600
	ds_read_b64_tr_b16 v[150:151], v246 offset:0x8e00
	v_mfma_f32_32x32x16_bf16 v[64:79], v[6:9], v[152:155], v[64:79]
	ds_read_b64_tr_b16 v[152:153], v246 offset:0xc600
	ds_read_b64_tr_b16 v[154:155], v246 offset:0xce00
	v_mfma_f32_32x32x16_bf16 v[48:63], v[10:13], v[156:159], v[48:63]
	ds_read_b64_tr_b16 v[156:157], v246 offset:0x9600
	ds_read_b64_tr_b16 v[158:159], v246 offset:0x9e00
	v_mfma_f32_32x32x16_bf16 v[64:79], v[10:13], v[160:163], v[64:79]
	ds_read_b64_tr_b16 v[160:161], v246 offset:0xd600
	ds_read_b64_tr_b16 v[162:163], v246 offset:0xde00
	v_mfma_f32_32x32x16_bf16 v[48:63], v[144:147], v[164:167], v[48:63]
	ds_read_b64_tr_b16 v[164:165], v246 offset:0xa600
	ds_read_b64_tr_b16 v[166:167], v246 offset:0xae00
	v_mfma_f32_32x32x16_bf16 v[64:79], v[144:147], v[168:171], v[64:79]
	ds_read_b64_tr_b16 v[168:169], v246 offset:0xe600
	ds_read_b64_tr_b16 v[170:171], v246 offset:0xee00
	v_mfma_f32_32x32x16_bf16 v[48:63], v[2:5], v[172:175], v[48:63]
	ds_read_b64_tr_b16 v[172:173], v246 offset:0xb600
	ds_read_b64_tr_b16 v[174:175], v246 offset:0xbe00
	v_mfma_f32_32x32x16_bf16 v[64:79], v[2:5], v[176:179], v[64:79]
	ds_read_b64_tr_b16 v[176:177], v246 offset:0xf600
	ds_read_b64_tr_b16 v[178:179], v246 offset:0xfe00
	s_waitcnt lgkmcnt(0)
	v_mfma_f32_32x32x16_bf16 v[16:31], v[6:9], v[148:151], v[16:31]
	s_waitcnt vmcnt(0) lgkmcnt(0)
	s_barrier
	s_add_u32 s68, s68, 0x4000
	s_addc_u32 s69, s69, 0
	s_add_u32 s98, s98, 0x4000
	s_addc_u32 s99, s99, 0
	s_add_u32 s100, s100, 0x4000
	s_addc_u32 s101, s101, 0
	s_add_i32 s90, s90, 64
	v_add_u32_e32 v247, 0xffffff00, v247
	v_mfma_f32_32x32x16_bf16 v[32:47], v[6:9], v[152:155], v[32:47]
	v_subrev_u32_e32 v248, 64, v248
	s_cmp_eq_u32 s88, s93
	v_mfma_f32_32x32x16_bf16 v[16:31], v[10:13], v[156:159], v[16:31]
	v_mfma_f32_32x32x16_bf16 v[32:47], v[10:13], v[160:163], v[32:47]
	v_mfma_f32_32x32x16_bf16 v[16:31], v[144:147], v[164:167], v[16:31]
	v_mfma_f32_32x32x16_bf16 v[32:47], v[144:147], v[168:171], v[32:47]
	v_mfma_f32_32x32x16_bf16 v[16:31], v[2:5], v[172:175], v[16:31]
	v_mfma_f32_32x32x16_bf16 v[32:47], v[2:5], v[176:179], v[32:47]
	s_cbranch_scc1 .LBB0_491
	s_branch .LBB0_449
